# resid-GEMM epilogue loads issued in a rolling window of 12 with counted vmcnt; conv_tile 4 row loads issued together
# speedup vs baseline: 1.0286x; 1.0286x over previous
.LBB0_19:
	s_movk_i32 s0, 0x17f
	v_cmp_lt_i32_e32 vcc, s0, v1
	s_mov_b64 s[38:39], 0
	s_and_saveexec_b64 s[0:1], vcc
	s_xor_b64 s[0:1], exec, s[0:1]
	s_cbranch_execz .LBB0_38
	v_add_u32_e32 v6, 0xfffffe80, v1
	v_mov_b64_e32 v[10:11], 0
	v_cmp_gt_u32_e32 vcc, s70, v6
	v_mov_b32_e32 v11, 0
	v_mov_b32_e32 v2, -1
	v_mov_b64_e32 v[12:13], 0
	v_mov_b64_e32 v[4:5], 0
	s_and_saveexec_b64 s[4:5], vcc
	v_mov_b64_e32 v[12:13], 0x400
	v_mov_b32_e32 v11, 0xc00
	v_mov_b64_e32 v[4:5], s[18:19]
	v_mov_b32_e32 v2, v6
	s_or_b64 exec, exec, s[4:5]
	s_movk_i32 s2, 0x2ff
	v_cmp_lt_u32_e32 vcc, s2, v6
	s_and_saveexec_b64 s[4:5], vcc
	v_mov_b64_e32 v[10:11], 0x300000
	v_add_u32_e32 v2, 0xfffffb80, v1
	v_mov_b64_e32 v[12:13], 0x400
	v_mov_b32_e32 v11, 0x400
	v_mov_b64_e32 v[4:5], s[34:35]
	s_or_b64 exec, exec, s[4:5]
	v_cmp_lt_i32_e32 vcc, -1, v2
	s_mov_b64 s[6:7], 0
	s_and_saveexec_b64 s[4:5], vcc
	s_cbranch_execz .LBB0_36
	v_add_u32_e32 v6, 63, v11
	v_lshrrev_b32_e32 v6, 6, v6
	v_cvt_f32_ubyte0_e32 v8, v6
	v_cvt_f32_u32_sdwa v7, v2 dst_sel:DWORD dst_unused:UNUSED_PAD src0_sel:WORD_0
	v_rcp_iflag_f32_e32 v9, v8
	v_mov_b32_e32 v13, v0
	v_mul_f32_e32 v9, v7, v9
	v_trunc_f32_e32 v9, v9
	v_cvt_u32_f32_e32 v14, v9
	v_fma_f32 v7, -v9, v8, v7
	v_cmp_ge_f32_e64 vcc, |v7|, v8
	v_mov_b32_e32 v8, 0
	v_mov_b32_e32 v9, 0
	v_addc_co_u32_e32 v7, vcc, 0, v14, vcc
	v_mul_lo_u16_e32 v6, v7, v6
	v_sub_u16_e32 v2, v2, v6
	v_lshlrev_b32_e32 v17, 6, v2
	v_lshlrev_b32_e32 v2, 2, v13
	v_and_b32_e32 v18, 60, v2
	v_or_b32_e32 v2, v17, v18
	v_cmp_lt_u32_e32 vcc, v2, v11
	v_lshlrev_b32_e32 v2, 2, v2
	v_lshlrev_b32_sdwa v16, v224, v7 dst_sel:DWORD dst_unused:UNUSED_PAD src0_sel:DWORD src1_sel:WORD_0
	v_lshl_add_u64 v[14:15], v[4:5], 0, v[2:3]
	v_bfe_u32 v2, v13, 4, 4
	v_mov_b32_e32 v4, 0
	v_mov_b32_e32 v6, 0
	v_mov_b32_e32 v7, 0
	v_mov_b32_e32 v80, 0
	v_mov_b32_e32 v81, 0
	v_mov_b32_e32 v82, 0
	v_mov_b32_e32 v83, 0
	v_mov_b32_e32 v84, 0
	v_mov_b32_e32 v85, 0
	v_mov_b32_e32 v86, 0
	v_mov_b32_e32 v87, 0
	v_mov_b32_e32 v88, 0
	v_mov_b32_e32 v89, 0
	v_mov_b32_e32 v90, 0
	v_mov_b32_e32 v91, 0
	v_mov_b32_e32 v92, 0
	v_mov_b32_e32 v93, 0
	v_mov_b32_e32 v94, 0
	v_mov_b32_e32 v95, 0
	s_and_saveexec_b64 s[6:7], vcc
	s_cbranch_execz .Lctp0_skip
	v_or_b32_e32 v5, v16, v2
	v_mul_hi_u32_u24_e32 v7, v5, v11
	v_mul_u32_u24_e32 v6, v5, v11
	v_lshl_add_u64 v[6:7], v[6:7], 2, v[14:15]
	global_load_dwordx4 v[80:83], v[6:7], off nt
	v_or3_b32 v5, v2, v16, 16
	v_mul_hi_u32_u24_e32 v7, v5, v11
	v_mul_u32_u24_e32 v6, v5, v11
	v_lshl_add_u64 v[6:7], v[6:7], 2, v[14:15]
	global_load_dwordx4 v[84:87], v[6:7], off nt
	v_or3_b32 v5, v2, v16, 32
	v_mul_hi_u32_u24_e32 v7, v5, v11
	v_mul_u32_u24_e32 v6, v5, v11
	v_lshl_add_u64 v[6:7], v[6:7], 2, v[14:15]
	global_load_dwordx4 v[88:91], v[6:7], off nt
	v_or3_b32 v5, v2, v16, 48
	v_mul_hi_u32_u24_e32 v7, v5, v11
	v_mul_u32_u24_e32 v6, v5, v11
	v_lshl_add_u64 v[6:7], v[6:7], 2, v[14:15]
	global_load_dwordx4 v[92:95], v[6:7], off nt
.Lctp0_skip:
	s_or_b64 exec, exec, s[6:7]
	v_mul_u32_u24_e32 v19, 0x104, v2
	v_lshlrev_b32_e32 v18, 2, v18
	v_add3_u32 v5, v28, v19, v18
	s_waitcnt vmcnt(3)
	ds_write2_b32 v5, v80, v81 offset1:1
	ds_write2_b32 v5, v82, v83 offset0:2 offset1:3
	v_add_u32_e32 v8, 0x1040, v5
	s_waitcnt vmcnt(2)
	ds_write2_b32 v8, v84, v85 offset1:1
	ds_write2_b32 v8, v86, v87 offset0:2 offset1:3
	v_add_u32_e32 v8, 0x2080, v5
	s_waitcnt vmcnt(1)
	ds_write2_b32 v8, v88, v89 offset1:1
	ds_write2_b32 v8, v90, v91 offset0:2 offset1:3
	v_add_u32_e32 v8, 0x30c0, v5
	s_waitcnt vmcnt(0)
	ds_write2_b32 v8, v92, v93 offset1:1
	ds_write2_b32 v8, v94, v95 offset0:2 offset1:3
	v_and_b32_e32 v4, 63, v13
	v_or_b32_e32 v5, v17, v4
	v_cmp_lt_u32_e32 vcc, v5, v11
	s_waitcnt lgkmcnt(0)
	s_barrier
	s_and_saveexec_b64 s[6:7], vcc
	s_cbranch_execz .LBB0_35
	v_lshlrev_b32_e32 v2, 1, v10
	v_lshl_add_u64 v[6:7], s[28:29], 0, v[2:3]
	v_lshrrev_b32_e32 v2, 3, v13
	v_mul_hi_i32_i24_e32 v9, v12, v5
	v_mul_i32_i24_e32 v8, v12, v5
	v_and_b32_e32 v13, 24, v2
	v_lshl_add_u64 v[6:7], v[8:9], 1, v[6:7]
	v_lshlrev_b32_e32 v2, 1, v16
	v_lshl_add_u64 v[8:9], v[6:7], 0, v[2:3]
	v_mul_u32_u24_e32 v2, 0x41, v13
	v_lshlrev_b32_e32 v2, 2, v2
	v_lshlrev_b32_e32 v4, 2, v4
	v_add3_u32 v15, v28, v4, v2
	v_add3_u32 v12, v28, v2, v4
	v_add_u32_e32 v2, 0x200, v15
	ds_read_b32 v14, v12
	ds_read2_b32 v[4:5], v15 offset0:65 offset1:130
	ds_read2_b32 v[6:7], v2 offset0:67 offset1:132
	v_add_u32_e32 v2, 0x400, v15
	ds_read2_b32 v[10:11], v2 offset0:69 offset1:134
	ds_read_b32 v2, v15 offset:1820
	ds_read_b32 v16, v15 offset:10140
	ds_read_b32 v17, v12 offset:8320
	v_add_u32_e32 v12, 0x2200, v15
	s_waitcnt lgkmcnt(5)
	v_cvt_pk_bf16_f32 v4, v14, v4
	s_waitcnt lgkmcnt(4)
	v_cvt_pk_bf16_f32 v5, v5, v6
	s_waitcnt lgkmcnt(3)
	v_cvt_pk_bf16_f32 v6, v7, v10
	v_add_u32_e32 v10, 0x2000, v15
	v_add_u32_e32 v14, 0x2400, v15
	s_waitcnt lgkmcnt(2)
	v_cvt_pk_bf16_f32 v7, v11, v2
	v_lshlrev_b32_e32 v2, 1, v13
	ds_read2_b32 v[10:11], v10 offset0:97 offset1:162
	ds_read2_b32 v[12:13], v12 offset0:99 offset1:164
	ds_read2_b32 v[14:15], v14 offset0:101 offset1:166
	v_lshl_add_u64 v[8:9], v[8:9], 0, v[2:3]
	global_store_dwordx4 v[8:9], v[4:7], off
	s_waitcnt lgkmcnt(2)
	s_nop 0
	v_cvt_pk_bf16_f32 v4, v17, v10
	s_waitcnt lgkmcnt(1)
	v_cvt_pk_bf16_f32 v5, v11, v12
	s_waitcnt lgkmcnt(0)
	v_cvt_pk_bf16_f32 v6, v13, v14
	v_cvt_pk_bf16_f32 v7, v15, v16
	global_store_dwordx4 v[8:9], v[4:7], off offset:64

.Lrk_tail:
	s_and_b64 vcc, exec, s[4:5]
	s_mov_b32 s55, s54
	s_waitcnt vmcnt(0)
	v_mov_b32_e32 v74, v156
	v_mov_b32_e32 v176, v157
	v_mov_b64_e32 v[4:5], v[172:173]
	v_mov_b64_e32 v[64:65], v[170:171]
	s_cbranch_vccnz .LBB0_210

.LBB0_81:
	s_add_i32 s1, 0, 0x10000
	v_add_u32_e32 v2, s1, v1
	ds_read_b128 v[82:85], v2
	ds_read_b128 v[150:153], v2 offset:1024
	ds_read_b128 v[158:161], v2 offset:2048
	ds_read_b128 v[178:181], v2 offset:3072
	s_cmp_eq_u32 s0, 18
	v_lshl_add_u64 v[66:67], v[64:65], 0, s[74:75]
	s_cselect_b64 vcc, -1, 0
	v_cndmask_b32_e32 v175, v67, v171, vcc
	v_cndmask_b32_e32 v174, v66, v170, vcc
	v_cndmask_b32_e32 v69, v63, v173, vcc
	v_cndmask_b32_e32 v68, v62, v172, vcc
	v_lshl_add_u64 v[76:77], v[64:65], 0, v[166:167]
	s_add_i32 m0, s19, 0xc000
	ds_read_b128 v[182:185], v155
	ds_read_b128 v[186:189], v155 offset:1024
	ds_read_b128 v[190:193], v155 offset:2048
	ds_read_b128 v[194:197], v155 offset:3072
	ds_read_b128 v[198:201], v155 offset:4096
	ds_read_b128 v[202:205], v155 offset:5120
	ds_read_b128 v[206:209], v155 offset:6144
	ds_read_b128 v[210:213], v155 offset:7168
	global_load_lds_dwordx4 v[76:77], off
	v_lshl_add_u64 v[64:65], v[64:65], 0, v[168:169]
	s_add_i32 m0, s19, 0xe000
	s_nop 0
	global_load_lds_dwordx4 v[64:65], off
	s_waitcnt lgkmcnt(8)
	s_barrier
	s_waitcnt lgkmcnt(0)
	s_setprio 1
	s_waitcnt lgkmcnt(0)
	v_mfma_f32_16x16x32_bf16 v[146:149], v[82:85], v[182:185], v[146:149]
	v_mfma_f32_16x16x32_bf16 v[142:145], v[158:161], v[182:185], v[142:145]
	v_mfma_f32_16x16x32_bf16 v[130:133], v[82:85], v[190:193], v[130:133]
	v_mfma_f32_16x16x32_bf16 v[126:129], v[158:161], v[190:193], v[126:129]
	v_mfma_f32_16x16x32_bf16 v[114:117], v[82:85], v[198:201], v[114:117]
	v_mfma_f32_16x16x32_bf16 v[110:113], v[158:161], v[198:201], v[110:113]
	v_mfma_f32_16x16x32_bf16 v[98:101], v[82:85], v[206:209], v[98:101]
	v_mfma_f32_16x16x32_bf16 v[94:97], v[158:161], v[206:209], v[94:97]
	v_mfma_f32_16x16x32_bf16 v[146:149], v[150:153], v[186:189], v[146:149]
	v_mfma_f32_16x16x32_bf16 v[142:145], v[178:181], v[186:189], v[142:145]
	v_mfma_f32_16x16x32_bf16 v[130:133], v[150:153], v[194:197], v[130:133]
	v_mfma_f32_16x16x32_bf16 v[126:129], v[178:181], v[194:197], v[126:129]
	v_mfma_f32_16x16x32_bf16 v[114:117], v[150:153], v[202:205], v[114:117]
	v_mfma_f32_16x16x32_bf16 v[110:113], v[178:181], v[202:205], v[110:113]
	v_mfma_f32_16x16x32_bf16 v[98:101], v[150:153], v[210:213], v[98:101]
	v_mfma_f32_16x16x32_bf16 v[94:97], v[178:181], v[210:213], v[94:97]
	s_setprio 0
	s_barrier
	s_add_i32 s6, 0, 0x14000
	s_add_i32 s1, s1, s18
	v_add_u32_e32 v2, s6, v1
	v_lshl_add_u64 v[64:65], v[68:69], 0, v[162:163]
	s_mov_b32 m0, s1
	ds_read_b128 v[214:217], v2
	ds_read_b128 v[234:237], v2 offset:1024
	ds_read_b128 v[238:241], v2 offset:2048
	ds_read_b128 v[242:245], v2 offset:3072
	global_load_lds_dwordx4 v[64:65], off
	v_lshl_add_u64 v[230:231], v[68:69], 0, v[164:165]
	s_add_i32 m0, s1, 0x2000
	s_nop 0
	global_load_lds_dwordx4 v[230:231], off
	s_barrier
	s_waitcnt lgkmcnt(0)
	s_setprio 1
	s_waitcnt lgkmcnt(0)
	v_mfma_f32_16x16x32_bf16 v[138:141], v[214:217], v[182:185], v[138:141]
	v_mfma_f32_16x16x32_bf16 v[134:137], v[238:241], v[182:185], v[134:137]
	v_mfma_f32_16x16x32_bf16 v[122:125], v[214:217], v[190:193], v[122:125]
	v_mfma_f32_16x16x32_bf16 v[118:121], v[238:241], v[190:193], v[118:121]
	v_mfma_f32_16x16x32_bf16 v[106:109], v[214:217], v[198:201], v[106:109]
	v_mfma_f32_16x16x32_bf16 v[102:105], v[238:241], v[198:201], v[102:105]
	v_mfma_f32_16x16x32_bf16 v[90:93], v[214:217], v[206:209], v[90:93]
	v_mfma_f32_16x16x32_bf16 v[86:89], v[238:241], v[206:209], v[86:89]
	v_mfma_f32_16x16x32_bf16 v[138:141], v[234:237], v[186:189], v[138:141]
	v_mfma_f32_16x16x32_bf16 v[134:137], v[242:245], v[186:189], v[134:137]
	v_mfma_f32_16x16x32_bf16 v[122:125], v[234:237], v[194:197], v[122:125]
	v_mfma_f32_16x16x32_bf16 v[118:121], v[242:245], v[194:197], v[118:121]
	v_mfma_f32_16x16x32_bf16 v[106:109], v[234:237], v[202:205], v[106:109]
	v_mfma_f32_16x16x32_bf16 v[102:105], v[242:245], v[202:205], v[102:105]
	v_mfma_f32_16x16x32_bf16 v[90:93], v[234:237], v[210:213], v[90:93]
	v_mfma_f32_16x16x32_bf16 v[86:89], v[242:245], v[210:213], v[86:89]
	s_setprio 0
	s_mov_b32 m0, s19
	v_lshl_add_u64 v[246:247], v[174:175], 0, v[162:163]
	s_barrier
	ds_read_b128 v[182:185], v155 offset:16384
	ds_read_b128 v[186:189], v155 offset:17408
	ds_read_b128 v[190:193], v155 offset:18432
	ds_read_b128 v[194:197], v155 offset:19456
	ds_read_b128 v[198:201], v155 offset:20480
	ds_read_b128 v[202:205], v155 offset:21504
	ds_read_b128 v[206:209], v155 offset:22528
	ds_read_b128 v[210:213], v155 offset:23552
	global_load_lds_dwordx4 v[246:247], off
	v_lshl_add_u64 v[248:249], v[174:175], 0, v[164:165]
	s_mov_b32 m0, s27
	s_nop 0
	global_load_lds_dwordx4 v[248:249], off
	s_barrier
	s_waitcnt lgkmcnt(0)
	s_setprio 1
	s_waitcnt lgkmcnt(0)
	v_mfma_f32_16x16x32_bf16 v[76:79], v[82:85], v[182:185], v[78:81]
	v_mfma_f32_16x16x32_bf16 v[70:73], v[158:161], v[182:185], v[70:73]
	v_mfma_f32_16x16x32_bf16 v[50:53], v[82:85], v[190:193], v[50:53]
	v_mfma_f32_16x16x32_bf16 v[46:49], v[158:161], v[190:193], v[46:49]
	v_mfma_f32_16x16x32_bf16 v[32:35], v[82:85], v[198:201], v[32:35]
	v_mfma_f32_16x16x32_bf16 v[28:31], v[158:161], v[198:201], v[28:31]
	v_mfma_f32_16x16x32_bf16 v[16:19], v[82:85], v[206:209], v[16:19]
	v_mfma_f32_16x16x32_bf16 v[12:15], v[158:161], v[206:209], v[12:15]
	v_mfma_f32_16x16x32_bf16 v[76:79], v[150:153], v[186:189], v[76:79]
	v_mfma_f32_16x16x32_bf16 v[70:73], v[178:181], v[186:189], v[70:73]
	v_mfma_f32_16x16x32_bf16 v[50:53], v[150:153], v[194:197], v[50:53]
	v_mfma_f32_16x16x32_bf16 v[46:49], v[178:181], v[194:197], v[46:49]
	v_mfma_f32_16x16x32_bf16 v[32:35], v[150:153], v[202:205], v[32:35]
	v_mfma_f32_16x16x32_bf16 v[28:31], v[178:181], v[202:205], v[28:31]
	v_mfma_f32_16x16x32_bf16 v[16:19], v[150:153], v[210:213], v[16:19]
	v_mfma_f32_16x16x32_bf16 v[12:15], v[178:181], v[210:213], v[12:15]
	s_setprio 0
	s_barrier
	v_lshl_add_u64 v[80:81], v[68:69], 0, s[14:15]
	s_add_i32 s1, s6, s18
	v_lshl_add_u64 v[82:83], v[80:81], 0, v[162:163]
	s_mov_b32 m0, s1
	v_lshl_add_u64 v[80:81], v[80:81], 0, v[164:165]
	global_load_lds_dwordx4 v[82:83], off
	s_add_i32 m0, s1, 0x2000
	s_nop 0
	global_load_lds_dwordx4 v[80:81], off
	s_waitcnt vmcnt(6)
	s_barrier
	s_setprio 1
	v_mfma_f32_16x16x32_bf16 v[58:61], v[214:217], v[182:185], v[58:61]
	v_mfma_f32_16x16x32_bf16 v[54:57], v[238:241], v[182:185], v[54:57]
	v_mfma_f32_16x16x32_bf16 v[42:45], v[214:217], v[190:193], v[42:45]
	v_mfma_f32_16x16x32_bf16 v[38:41], v[238:241], v[190:193], v[38:41]
	v_mfma_f32_16x16x32_bf16 v[24:27], v[214:217], v[198:201], v[24:27]
	v_mfma_f32_16x16x32_bf16 v[20:23], v[238:241], v[198:201], v[20:23]
	v_mfma_f32_16x16x32_bf16 v[8:11], v[214:217], v[206:209], v[8:11]
	v_mfma_f32_16x16x32_bf16 v[4:7], v[238:241], v[206:209], v[4:7]
	v_mfma_f32_16x16x32_bf16 v[58:61], v[234:237], v[186:189], v[58:61]
	v_mfma_f32_16x16x32_bf16 v[54:57], v[242:245], v[186:189], v[54:57]
	v_mfma_f32_16x16x32_bf16 v[42:45], v[234:237], v[194:197], v[42:45]
	v_mfma_f32_16x16x32_bf16 v[38:41], v[242:245], v[194:197], v[38:41]
	v_mfma_f32_16x16x32_bf16 v[24:27], v[234:237], v[202:205], v[24:27]
	v_mfma_f32_16x16x32_bf16 v[20:23], v[242:245], v[202:205], v[20:23]
	v_mfma_f32_16x16x32_bf16 v[8:11], v[234:237], v[210:213], v[8:11]
	v_mfma_f32_16x16x32_bf16 v[4:7], v[242:245], v[210:213], v[4:7]
	s_setprio 0
	s_add_i32 s1, 0, 0x18000
	v_add_u32_e32 v2, s1, v1
	s_barrier
	ds_read_b128 v[82:85], v2
	ds_read_b128 v[150:153], v2 offset:1024
	ds_read_b128 v[158:161], v2 offset:2048
	ds_read_b128 v[178:181], v2 offset:3072
	v_lshl_add_u64 v[80:81], v[174:175], 0, s[14:15]
	s_mov_b32 m0, s45
	v_lshl_add_u64 v[174:175], v[80:81], 0, v[162:163]
	ds_read_b128 v[182:185], v155 offset:32768
	ds_read_b128 v[186:189], v155 offset:33792
	ds_read_b128 v[190:193], v155 offset:34816
	ds_read_b128 v[194:197], v155 offset:35840
	ds_read_b128 v[198:201], v155 offset:36864
	ds_read_b128 v[202:205], v155 offset:37888
	ds_read_b128 v[206:209], v155 offset:38912
	ds_read_b128 v[210:213], v155 offset:39936
	global_load_lds_dwordx4 v[174:175], off
	v_lshl_add_u64 v[80:81], v[80:81], 0, v[164:165]
	s_mov_b32 m0, s46
	s_nop 0
	global_load_lds_dwordx4 v[80:81], off
	s_waitcnt lgkmcnt(8)
	s_barrier
	s_waitcnt lgkmcnt(0)
	s_setprio 1
	s_waitcnt lgkmcnt(0)
	v_mfma_f32_16x16x32_bf16 v[146:149], v[82:85], v[182:185], v[146:149]
	v_mfma_f32_16x16x32_bf16 v[142:145], v[158:161], v[182:185], v[142:145]
	v_mfma_f32_16x16x32_bf16 v[130:133], v[82:85], v[190:193], v[130:133]
	v_mfma_f32_16x16x32_bf16 v[126:129], v[158:161], v[190:193], v[126:129]
	v_mfma_f32_16x16x32_bf16 v[114:117], v[82:85], v[198:201], v[114:117]
	v_mfma_f32_16x16x32_bf16 v[110:113], v[158:161], v[198:201], v[110:113]
	v_mfma_f32_16x16x32_bf16 v[98:101], v[82:85], v[206:209], v[98:101]
	v_mfma_f32_16x16x32_bf16 v[94:97], v[158:161], v[206:209], v[94:97]
	v_mfma_f32_16x16x32_bf16 v[146:149], v[150:153], v[186:189], v[146:149]
	v_mfma_f32_16x16x32_bf16 v[142:145], v[178:181], v[186:189], v[142:145]
	v_mfma_f32_16x16x32_bf16 v[130:133], v[150:153], v[194:197], v[130:133]
	v_mfma_f32_16x16x32_bf16 v[126:129], v[178:181], v[194:197], v[126:129]
	v_mfma_f32_16x16x32_bf16 v[114:117], v[150:153], v[202:205], v[114:117]
	v_mfma_f32_16x16x32_bf16 v[110:113], v[178:181], v[202:205], v[110:113]
	v_mfma_f32_16x16x32_bf16 v[98:101], v[150:153], v[210:213], v[98:101]
	v_mfma_f32_16x16x32_bf16 v[94:97], v[178:181], v[210:213], v[94:97]
	s_setprio 0
	s_barrier
	s_add_i32 s6, 0, 0x1c000
	s_add_i32 s1, s1, s18
	v_add_u32_e32 v2, s6, v1
	v_lshl_add_u64 v[64:65], v[64:65], 0, s[24:25]
	s_mov_b32 m0, s1
	ds_read_b128 v[214:217], v2
	ds_read_b128 v[234:237], v2 offset:1024
	ds_read_b128 v[238:241], v2 offset:2048
	ds_read_b128 v[242:245], v2 offset:3072
	global_load_lds_dwordx4 v[64:65], off
	v_lshl_add_u64 v[64:65], v[230:231], 0, s[24:25]
	s_add_i32 m0, s1, 0x2000
	s_nop 0
	global_load_lds_dwordx4 v[64:65], off
	s_barrier
	s_waitcnt lgkmcnt(0)
	s_setprio 1
	s_waitcnt lgkmcnt(0)
	v_mfma_f32_16x16x32_bf16 v[138:141], v[214:217], v[182:185], v[138:141]
	v_mfma_f32_16x16x32_bf16 v[134:137], v[238:241], v[182:185], v[134:137]
	v_mfma_f32_16x16x32_bf16 v[122:125], v[214:217], v[190:193], v[122:125]
	v_mfma_f32_16x16x32_bf16 v[118:121], v[238:241], v[190:193], v[118:121]
	v_mfma_f32_16x16x32_bf16 v[106:109], v[214:217], v[198:201], v[106:109]
	v_mfma_f32_16x16x32_bf16 v[102:105], v[238:241], v[198:201], v[102:105]
	v_mfma_f32_16x16x32_bf16 v[90:93], v[214:217], v[206:209], v[90:93]
	v_mfma_f32_16x16x32_bf16 v[86:89], v[238:241], v[206:209], v[86:89]
	v_mfma_f32_16x16x32_bf16 v[138:141], v[234:237], v[186:189], v[138:141]
	v_mfma_f32_16x16x32_bf16 v[134:137], v[242:245], v[186:189], v[134:137]
	v_mfma_f32_16x16x32_bf16 v[122:125], v[234:237], v[194:197], v[122:125]
	v_mfma_f32_16x16x32_bf16 v[118:121], v[242:245], v[194:197], v[118:121]
	v_mfma_f32_16x16x32_bf16 v[106:109], v[234:237], v[202:205], v[106:109]
	v_mfma_f32_16x16x32_bf16 v[102:105], v[242:245], v[202:205], v[102:105]
	v_mfma_f32_16x16x32_bf16 v[90:93], v[234:237], v[210:213], v[90:93]
	v_mfma_f32_16x16x32_bf16 v[86:89], v[242:245], v[210:213], v[86:89]
	s_setprio 0
	s_mov_b32 m0, s47
	v_lshl_add_u64 v[64:65], v[246:247], 0, s[24:25]
	s_barrier
	ds_read_b128 v[182:185], v155 offset:49152
	ds_read_b128 v[186:189], v155 offset:50176
	ds_read_b128 v[190:193], v155 offset:51200
	ds_read_b128 v[194:197], v155 offset:52224
	ds_read_b128 v[198:201], v155 offset:53248
	ds_read_b128 v[202:205], v155 offset:54272
	ds_read_b128 v[206:209], v155 offset:55296
	ds_read_b128 v[210:213], v155 offset:56320
	global_load_lds_dwordx4 v[64:65], off
	v_lshl_add_u64 v[64:65], v[248:249], 0, s[24:25]
	s_mov_b32 m0, s48
	s_nop 0
	global_load_lds_dwordx4 v[64:65], off
	s_barrier
	s_waitcnt lgkmcnt(0)
	s_setprio 1
	s_waitcnt lgkmcnt(0)
	v_mfma_f32_16x16x32_bf16 v[76:79], v[82:85], v[182:185], v[76:79]
	v_mfma_f32_16x16x32_bf16 v[70:73], v[158:161], v[182:185], v[70:73]
	v_mfma_f32_16x16x32_bf16 v[50:53], v[82:85], v[190:193], v[50:53]
	v_mfma_f32_16x16x32_bf16 v[46:49], v[158:161], v[190:193], v[46:49]
	v_mfma_f32_16x16x32_bf16 v[32:35], v[82:85], v[198:201], v[32:35]
	v_mfma_f32_16x16x32_bf16 v[28:31], v[158:161], v[198:201], v[28:31]
	v_mfma_f32_16x16x32_bf16 v[16:19], v[82:85], v[206:209], v[16:19]
	v_mfma_f32_16x16x32_bf16 v[12:15], v[158:161], v[206:209], v[12:15]
	v_mfma_f32_16x16x32_bf16 v[78:81], v[150:153], v[186:189], v[76:79]
	v_mfma_f32_16x16x32_bf16 v[70:73], v[178:181], v[186:189], v[70:73]
	v_mfma_f32_16x16x32_bf16 v[50:53], v[150:153], v[194:197], v[50:53]
	v_mfma_f32_16x16x32_bf16 v[46:49], v[178:181], v[194:197], v[46:49]
	v_mfma_f32_16x16x32_bf16 v[32:35], v[150:153], v[202:205], v[32:35]
	v_mfma_f32_16x16x32_bf16 v[28:31], v[178:181], v[202:205], v[28:31]
	v_mfma_f32_16x16x32_bf16 v[16:19], v[150:153], v[210:213], v[16:19]
	v_mfma_f32_16x16x32_bf16 v[12:15], v[178:181], v[210:213], v[12:15]
	s_setprio 0
	s_barrier
	v_lshl_add_u64 v[64:65], v[68:69], 0, s[40:41]
	s_add_i32 s1, s6, s18
	v_lshl_add_u64 v[68:69], v[64:65], 0, v[162:163]
	s_mov_b32 m0, s1
	v_lshl_add_u64 v[64:65], v[64:65], 0, v[164:165]
	global_load_lds_dwordx4 v[68:69], off
	s_add_i32 m0, s1, 0x2000
	s_nop 0
	global_load_lds_dwordx4 v[64:65], off
	s_waitcnt vmcnt(6)
	s_barrier
	s_setprio 1
	v_mfma_f32_16x16x32_bf16 v[58:61], v[214:217], v[182:185], v[58:61]
	v_mfma_f32_16x16x32_bf16 v[54:57], v[238:241], v[182:185], v[54:57]
	v_mfma_f32_16x16x32_bf16 v[42:45], v[214:217], v[190:193], v[42:45]
	v_mfma_f32_16x16x32_bf16 v[38:41], v[238:241], v[190:193], v[38:41]
	v_mfma_f32_16x16x32_bf16 v[24:27], v[214:217], v[198:201], v[24:27]
	v_mfma_f32_16x16x32_bf16 v[20:23], v[238:241], v[198:201], v[20:23]
	v_mfma_f32_16x16x32_bf16 v[8:11], v[214:217], v[206:209], v[8:11]
	v_mfma_f32_16x16x32_bf16 v[4:7], v[238:241], v[206:209], v[4:7]
	v_mfma_f32_16x16x32_bf16 v[58:61], v[234:237], v[186:189], v[58:61]
	v_mfma_f32_16x16x32_bf16 v[54:57], v[242:245], v[186:189], v[54:57]
	v_mfma_f32_16x16x32_bf16 v[42:45], v[234:237], v[194:197], v[42:45]
	v_mfma_f32_16x16x32_bf16 v[38:41], v[242:245], v[194:197], v[38:41]
	v_mfma_f32_16x16x32_bf16 v[24:27], v[234:237], v[202:205], v[24:27]
	v_mfma_f32_16x16x32_bf16 v[20:23], v[242:245], v[202:205], v[20:23]
	v_mfma_f32_16x16x32_bf16 v[8:11], v[234:237], v[210:213], v[8:11]
	v_mfma_f32_16x16x32_bf16 v[4:7], v[242:245], v[210:213], v[4:7]
	s_setprio 0
	s_add_i32 s0, s0, 2
	v_lshl_add_u64 v[62:63], v[62:63], 0, s[74:75]
	s_cmp_gt_u32 s0, 19
	v_mov_b64_e32 v[64:65], v[66:67]
	s_barrier
	s_cbranch_scc0 .LBB0_81
	v_cmp_gt_i32_e32 vcc, 24, v176
	v_mov_b32_e32 v2, 0x3000
	v_mov_b32_e32 v62, 0x1800
	v_cndmask_b32_e32 v2, v2, v62, vcc
	v_cmp_lt_i32_e32 vcc, 15, v176
	v_lshl_or_b32 v150, v74, 8, v154
	v_ashrrev_i32_e32 v151, 31, v150
	v_cndmask_b32_e32 v2, 0, v2, vcc
	v_lshlrev_b32_e32 v2, 2, v2
	v_lshl_add_u64 v[62:63], s[12:13], 0, v[2:3]
	v_lshl_add_u64 v[62:63], v[150:151], 2, v[62:63]
	global_load_dwordx4 v[82:85], v[62:63], off
	global_load_dwordx4 v[74:77], v[62:63], off offset:64
	global_load_dwordx4 v[66:69], v[62:63], off offset:512
	s_nop 0
	global_load_dwordx4 v[62:65], v[62:63], off offset:576
	s_cmp_eq_u32 s55, 0
	s_cselect_b64 s[6:7], -1, 0
	s_cmp_lg_u32 s55, 0
	s_mov_b64 s[40:41], 0xb0000
	s_cselect_b64 s[0:1], -1, 0
	v_add_u32_e32 v174, v37, v150
	v_mov_b32_e32 v175, v3
	v_lshlrev_b32_e32 v158, 8, v176
	v_ashrrev_i32_e32 v159, 31, v158
	v_lshlrev_b64 v[178:179], 12, v[158:159]
	v_lshl_add_u64 v[176:177], s[8:9], 0, v[178:179]
	s_and_b64 s[6:7], exec, s[6:7]
	s_cselect_b32 s7, s9, s35
	s_cselect_b32 s6, s8, s34
	v_lshl_add_u64 v[178:179], s[6:7], 0, v[178:179]
	s_and_b64 vcc, exec, s[0:1]
	s_cbranch_vccnz .Lrk_mul
	v_mov_b32_e32 v150, v174
	v_mov_b32_e32 v151, v3
	v_lshl_add_u64 v[152:153], v[150:151], 2, v[176:177]
	global_load_dwordx4 v[182:185], v[152:153], off
	global_load_dwordx4 v[186:189], v[152:153], off offset:64
	global_load_dwordx4 v[190:193], v[152:153], off offset:512
	global_load_dwordx4 v[194:197], v[152:153], off offset:576
	v_add_u32_e32 v150, 0x4000, v174
	v_mov_b32_e32 v151, v3
	v_lshl_add_u64 v[152:153], v[150:151], 2, v[176:177]
	global_load_dwordx4 v[198:201], v[152:153], off
	global_load_dwordx4 v[202:205], v[152:153], off offset:64
	global_load_dwordx4 v[206:209], v[152:153], off offset:512
	global_load_dwordx4 v[210:213], v[152:153], off offset:576
	v_add_u32_e32 v150, 0x8000, v174
	v_mov_b32_e32 v151, v3
	v_lshl_add_u64 v[152:153], v[150:151], 2, v[176:177]
	global_load_dwordx4 v[214:217], v[152:153], off
	global_load_dwordx4 v[234:237], v[152:153], off offset:64
	global_load_dwordx4 v[238:241], v[152:153], off offset:512
	global_load_dwordx4 v[242:245], v[152:153], off offset:576
	v_mov_b32_e32 v150, v174
	v_mov_b32_e32 v151, v3
	v_lshl_add_u64 v[158:159], v[150:151], 2, v[178:179]
	s_waitcnt vmcnt(11)
	v_pk_fma_f32 v[148:149], v[148:149], v[84:85], v[184:185]
	v_pk_fma_f32 v[146:147], v[146:147], v[82:83], v[182:183]
	global_store_dwordx4 v[158:159], v[146:149], off
	v_add_u32_e32 v150, 0xc000, v174
	v_mov_b32_e32 v151, v3
	v_lshl_add_u64 v[152:153], v[150:151], 2, v[176:177]
	global_load_dwordx4 v[182:185], v[152:153], off
	s_waitcnt vmcnt(12)
	v_pk_fma_f32 v[144:145], v[144:145], v[76:77], v[188:189]
	v_pk_fma_f32 v[142:143], v[142:143], v[74:75], v[186:187]
	global_store_dwordx4 v[158:159], v[142:145], off offset:64
	global_load_dwordx4 v[186:189], v[152:153], off offset:64
	s_waitcnt vmcnt(13)
	v_pk_fma_f32 v[140:141], v[140:141], v[68:69], v[192:193]
	v_pk_fma_f32 v[138:139], v[138:139], v[66:67], v[190:191]
	global_store_dwordx4 v[158:159], v[138:141], off offset:512
	global_load_dwordx4 v[190:193], v[152:153], off offset:512
	s_waitcnt vmcnt(14)
	v_pk_fma_f32 v[136:137], v[136:137], v[64:65], v[196:197]
	v_pk_fma_f32 v[134:135], v[134:135], v[62:63], v[194:195]
	global_store_dwordx4 v[158:159], v[134:137], off offset:576
	global_load_dwordx4 v[194:197], v[152:153], off offset:576
	v_add_u32_e32 v150, 0x4000, v174
	v_mov_b32_e32 v151, v3
	v_lshl_add_u64 v[158:159], v[150:151], 2, v[178:179]
	s_waitcnt vmcnt(15)
	v_pk_fma_f32 v[132:133], v[132:133], v[84:85], v[200:201]
	v_pk_fma_f32 v[130:131], v[130:131], v[82:83], v[198:199]
	global_store_dwordx4 v[158:159], v[130:133], off
	v_add_u32_e32 v150, 0x20000, v174
	v_mov_b32_e32 v151, v3
	v_lshl_add_u64 v[152:153], v[150:151], 2, v[176:177]
	global_load_dwordx4 v[198:201], v[152:153], off
	s_waitcnt vmcnt(16)
	v_pk_fma_f32 v[128:129], v[128:129], v[76:77], v[204:205]
	v_pk_fma_f32 v[126:127], v[126:127], v[74:75], v[202:203]
	global_store_dwordx4 v[158:159], v[126:129], off offset:64
	global_load_dwordx4 v[202:205], v[152:153], off offset:64
	s_waitcnt vmcnt(17)
	v_pk_fma_f32 v[124:125], v[124:125], v[68:69], v[208:209]
	v_pk_fma_f32 v[122:123], v[122:123], v[66:67], v[206:207]
	global_store_dwordx4 v[158:159], v[122:125], off offset:512
	global_load_dwordx4 v[206:209], v[152:153], off offset:512
	s_waitcnt vmcnt(18)
	v_pk_fma_f32 v[120:121], v[120:121], v[64:65], v[212:213]
	v_pk_fma_f32 v[118:119], v[118:119], v[62:63], v[210:211]
	global_store_dwordx4 v[158:159], v[118:121], off offset:576
	global_load_dwordx4 v[210:213], v[152:153], off offset:576
	v_add_u32_e32 v150, 0x8000, v174
	v_mov_b32_e32 v151, v3
	v_lshl_add_u64 v[158:159], v[150:151], 2, v[178:179]
	s_waitcnt vmcnt(19)
	v_pk_fma_f32 v[116:117], v[116:117], v[84:85], v[216:217]
	v_pk_fma_f32 v[114:115], v[114:115], v[82:83], v[214:215]
	global_store_dwordx4 v[158:159], v[114:117], off
	v_add_u32_e32 v150, 0x24000, v174
	v_mov_b32_e32 v151, v3
	v_lshl_add_u64 v[152:153], v[150:151], 2, v[176:177]
	global_load_dwordx4 v[214:217], v[152:153], off
	s_waitcnt vmcnt(20)
	v_pk_fma_f32 v[112:113], v[112:113], v[76:77], v[236:237]
	v_pk_fma_f32 v[110:111], v[110:111], v[74:75], v[234:235]
	global_store_dwordx4 v[158:159], v[110:113], off offset:64
	global_load_dwordx4 v[234:237], v[152:153], off offset:64
	s_waitcnt vmcnt(21)
	v_pk_fma_f32 v[108:109], v[108:109], v[68:69], v[240:241]
	v_pk_fma_f32 v[106:107], v[106:107], v[66:67], v[238:239]
	global_store_dwordx4 v[158:159], v[106:109], off offset:512
	global_load_dwordx4 v[238:241], v[152:153], off offset:512
	s_waitcnt vmcnt(22)
	v_pk_fma_f32 v[104:105], v[104:105], v[64:65], v[244:245]
	v_pk_fma_f32 v[102:103], v[102:103], v[62:63], v[242:243]
	global_store_dwordx4 v[158:159], v[102:105], off offset:576
	global_load_dwordx4 v[242:245], v[152:153], off offset:576
	v_add_u32_e32 v150, 0xc000, v174
	v_mov_b32_e32 v151, v3
	v_lshl_add_u64 v[158:159], v[150:151], 2, v[178:179]
	s_waitcnt vmcnt(22)
	v_pk_fma_f32 v[100:101], v[100:101], v[84:85], v[184:185]
	v_pk_fma_f32 v[98:99], v[98:99], v[82:83], v[182:183]
	global_store_dwordx4 v[158:159], v[98:101], off
	v_add_u32_e32 v150, 0x28000, v174
	v_mov_b32_e32 v151, v3
	v_lshl_add_u64 v[152:153], v[150:151], 2, v[176:177]
	global_load_dwordx4 v[182:185], v[152:153], off
	s_waitcnt vmcnt(22)
	v_pk_fma_f32 v[96:97], v[96:97], v[76:77], v[188:189]
	v_pk_fma_f32 v[94:95], v[94:95], v[74:75], v[186:187]
	global_store_dwordx4 v[158:159], v[94:97], off offset:64
	global_load_dwordx4 v[186:189], v[152:153], off offset:64
	s_waitcnt vmcnt(22)
	v_pk_fma_f32 v[92:93], v[92:93], v[68:69], v[192:193]
	v_pk_fma_f32 v[90:91], v[90:91], v[66:67], v[190:191]
	global_store_dwordx4 v[158:159], v[90:93], off offset:512
	global_load_dwordx4 v[190:193], v[152:153], off offset:512
	s_waitcnt vmcnt(22)
	v_pk_fma_f32 v[88:89], v[88:89], v[64:65], v[196:197]
	v_pk_fma_f32 v[86:87], v[86:87], v[62:63], v[194:195]
	global_store_dwordx4 v[158:159], v[86:89], off offset:576
	global_load_dwordx4 v[194:197], v[152:153], off offset:576
	v_add_u32_e32 v150, 0x20000, v174
	v_mov_b32_e32 v151, v3
	v_lshl_add_u64 v[158:159], v[150:151], 2, v[178:179]
	s_waitcnt vmcnt(22)
	v_pk_fma_f32 v[80:81], v[80:81], v[84:85], v[200:201]
	v_pk_fma_f32 v[78:79], v[78:79], v[82:83], v[198:199]
	global_store_dwordx4 v[158:159], v[78:81], off
	v_add_u32_e32 v150, 0x2c000, v174
	v_mov_b32_e32 v151, v3
	v_lshl_add_u64 v[152:153], v[150:151], 2, v[176:177]
	global_load_dwordx4 v[198:201], v[152:153], off
	s_waitcnt vmcnt(22)
	v_pk_fma_f32 v[72:73], v[72:73], v[76:77], v[204:205]
	v_pk_fma_f32 v[70:71], v[70:71], v[74:75], v[202:203]
	global_store_dwordx4 v[158:159], v[70:73], off offset:64
	global_load_dwordx4 v[202:205], v[152:153], off offset:64
	s_waitcnt vmcnt(22)
	v_pk_fma_f32 v[60:61], v[60:61], v[68:69], v[208:209]
	v_pk_fma_f32 v[58:59], v[58:59], v[66:67], v[206:207]
	global_store_dwordx4 v[158:159], v[58:61], off offset:512
	global_load_dwordx4 v[206:209], v[152:153], off offset:512
	s_waitcnt vmcnt(22)
	v_pk_fma_f32 v[56:57], v[56:57], v[64:65], v[212:213]
	v_pk_fma_f32 v[54:55], v[54:55], v[62:63], v[210:211]
	global_store_dwordx4 v[158:159], v[54:57], off offset:576
	global_load_dwordx4 v[210:213], v[152:153], off offset:576
	v_add_u32_e32 v150, 0x24000, v174
	v_mov_b32_e32 v151, v3
	v_lshl_add_u64 v[158:159], v[150:151], 2, v[178:179]
	s_waitcnt vmcnt(22)
	v_pk_fma_f32 v[52:53], v[52:53], v[84:85], v[216:217]
	v_pk_fma_f32 v[50:51], v[50:51], v[82:83], v[214:215]
	global_store_dwordx4 v[158:159], v[50:53], off
	s_waitcnt vmcnt(21)
	v_pk_fma_f32 v[48:49], v[48:49], v[76:77], v[236:237]
	v_pk_fma_f32 v[46:47], v[46:47], v[74:75], v[234:235]
	global_store_dwordx4 v[158:159], v[46:49], off offset:64
	s_waitcnt vmcnt(20)
	v_pk_fma_f32 v[44:45], v[44:45], v[68:69], v[240:241]
	v_pk_fma_f32 v[42:43], v[42:43], v[66:67], v[238:239]
	global_store_dwordx4 v[158:159], v[42:45], off offset:512
	s_waitcnt vmcnt(19)
	v_pk_fma_f32 v[40:41], v[40:41], v[64:65], v[244:245]
	v_pk_fma_f32 v[38:39], v[38:39], v[62:63], v[242:243]
	global_store_dwordx4 v[158:159], v[38:41], off offset:576
	v_add_u32_e32 v150, 0x28000, v174
	v_mov_b32_e32 v151, v3
	v_lshl_add_u64 v[158:159], v[150:151], 2, v[178:179]
	s_waitcnt vmcnt(18)
	v_pk_fma_f32 v[34:35], v[34:35], v[84:85], v[184:185]
	v_pk_fma_f32 v[32:33], v[32:33], v[82:83], v[182:183]
	global_store_dwordx4 v[158:159], v[32:35], off
	s_waitcnt vmcnt(17)
	v_pk_fma_f32 v[30:31], v[30:31], v[76:77], v[188:189]
	v_pk_fma_f32 v[28:29], v[28:29], v[74:75], v[186:187]
	global_store_dwordx4 v[158:159], v[28:31], off offset:64
	s_waitcnt vmcnt(16)
	v_pk_fma_f32 v[26:27], v[26:27], v[68:69], v[192:193]
	v_pk_fma_f32 v[24:25], v[24:25], v[66:67], v[190:191]
	global_store_dwordx4 v[158:159], v[24:27], off offset:512
	s_waitcnt vmcnt(15)
	v_pk_fma_f32 v[22:23], v[22:23], v[64:65], v[196:197]
	v_pk_fma_f32 v[20:21], v[20:21], v[62:63], v[194:195]
	global_store_dwordx4 v[158:159], v[20:23], off offset:576
	v_add_u32_e32 v150, 0x2c000, v174
	v_mov_b32_e32 v151, v3
	v_lshl_add_u64 v[158:159], v[150:151], 2, v[178:179]
	s_waitcnt vmcnt(14)
	v_pk_fma_f32 v[18:19], v[18:19], v[84:85], v[200:201]
	v_pk_fma_f32 v[16:17], v[16:17], v[82:83], v[198:199]
	global_store_dwordx4 v[158:159], v[16:19], off
	s_waitcnt vmcnt(13)
	v_pk_fma_f32 v[14:15], v[14:15], v[76:77], v[204:205]
	v_pk_fma_f32 v[12:13], v[12:13], v[74:75], v[202:203]
	global_store_dwordx4 v[158:159], v[12:15], off offset:64
	s_waitcnt vmcnt(12)
	v_pk_fma_f32 v[10:11], v[10:11], v[68:69], v[208:209]
	v_pk_fma_f32 v[8:9], v[8:9], v[66:67], v[206:207]
	global_store_dwordx4 v[158:159], v[8:11], off offset:512
	s_waitcnt vmcnt(11)
	v_pk_fma_f32 v[6:7], v[6:7], v[64:65], v[212:213]
	v_pk_fma_f32 v[4:5], v[4:5], v[62:63], v[210:211]
	global_store_dwordx4 v[158:159], v[4:7], off offset:576
	s_branch .Lrk_tail
.Lrk_mul:
	s_waitcnt vmcnt(0)
	v_mov_b32_e32 v150, v174
	v_mov_b32_e32 v151, v3
	v_lshl_add_u64 v[158:159], v[150:151], 2, v[178:179]
	v_pk_mul_f32 v[148:149], v[148:149], v[84:85]
	v_pk_mul_f32 v[146:147], v[146:147], v[82:83]
	global_store_dwordx4 v[158:159], v[146:149], off
	v_pk_mul_f32 v[144:145], v[144:145], v[76:77]
	v_pk_mul_f32 v[142:143], v[142:143], v[74:75]
	global_store_dwordx4 v[158:159], v[142:145], off offset:64
	v_pk_mul_f32 v[140:141], v[140:141], v[68:69]
	v_pk_mul_f32 v[138:139], v[138:139], v[66:67]
	global_store_dwordx4 v[158:159], v[138:141], off offset:512
	v_pk_mul_f32 v[136:137], v[136:137], v[64:65]
	v_pk_mul_f32 v[134:135], v[134:135], v[62:63]
	global_store_dwordx4 v[158:159], v[134:137], off offset:576
	v_add_u32_e32 v150, 0x4000, v174
	v_mov_b32_e32 v151, v3
	v_lshl_add_u64 v[158:159], v[150:151], 2, v[178:179]
	v_pk_mul_f32 v[132:133], v[132:133], v[84:85]
	v_pk_mul_f32 v[130:131], v[130:131], v[82:83]
	global_store_dwordx4 v[158:159], v[130:133], off
	v_pk_mul_f32 v[128:129], v[128:129], v[76:77]
	v_pk_mul_f32 v[126:127], v[126:127], v[74:75]
	global_store_dwordx4 v[158:159], v[126:129], off offset:64
	v_pk_mul_f32 v[124:125], v[124:125], v[68:69]
	v_pk_mul_f32 v[122:123], v[122:123], v[66:67]
	global_store_dwordx4 v[158:159], v[122:125], off offset:512
	v_pk_mul_f32 v[120:121], v[120:121], v[64:65]
	v_pk_mul_f32 v[118:119], v[118:119], v[62:63]
	global_store_dwordx4 v[158:159], v[118:121], off offset:576
	v_add_u32_e32 v150, 0x8000, v174
	v_mov_b32_e32 v151, v3
	v_lshl_add_u64 v[158:159], v[150:151], 2, v[178:179]
	v_pk_mul_f32 v[116:117], v[116:117], v[84:85]
	v_pk_mul_f32 v[114:115], v[114:115], v[82:83]
	global_store_dwordx4 v[158:159], v[114:117], off
	v_pk_mul_f32 v[112:113], v[112:113], v[76:77]
	v_pk_mul_f32 v[110:111], v[110:111], v[74:75]
	global_store_dwordx4 v[158:159], v[110:113], off offset:64
	v_pk_mul_f32 v[108:109], v[108:109], v[68:69]
	v_pk_mul_f32 v[106:107], v[106:107], v[66:67]
	global_store_dwordx4 v[158:159], v[106:109], off offset:512
	v_pk_mul_f32 v[104:105], v[104:105], v[64:65]
	v_pk_mul_f32 v[102:103], v[102:103], v[62:63]
	global_store_dwordx4 v[158:159], v[102:105], off offset:576
	v_add_u32_e32 v150, 0xc000, v174
	v_mov_b32_e32 v151, v3
	v_lshl_add_u64 v[158:159], v[150:151], 2, v[178:179]
	v_pk_mul_f32 v[100:101], v[100:101], v[84:85]
	v_pk_mul_f32 v[98:99], v[98:99], v[82:83]
	global_store_dwordx4 v[158:159], v[98:101], off
	v_pk_mul_f32 v[96:97], v[96:97], v[76:77]
	v_pk_mul_f32 v[94:95], v[94:95], v[74:75]
	global_store_dwordx4 v[158:159], v[94:97], off offset:64
	v_pk_mul_f32 v[92:93], v[92:93], v[68:69]
	v_pk_mul_f32 v[90:91], v[90:91], v[66:67]
	global_store_dwordx4 v[158:159], v[90:93], off offset:512
	v_pk_mul_f32 v[88:89], v[88:89], v[64:65]
	v_pk_mul_f32 v[86:87], v[86:87], v[62:63]
	global_store_dwordx4 v[158:159], v[86:89], off offset:576
	v_add_u32_e32 v150, 0x20000, v174
	v_mov_b32_e32 v151, v3
	v_lshl_add_u64 v[158:159], v[150:151], 2, v[178:179]
	v_pk_mul_f32 v[80:81], v[80:81], v[84:85]
	v_pk_mul_f32 v[78:79], v[78:79], v[82:83]
	global_store_dwordx4 v[158:159], v[78:81], off
	v_pk_mul_f32 v[72:73], v[72:73], v[76:77]
	v_pk_mul_f32 v[70:71], v[70:71], v[74:75]
	global_store_dwordx4 v[158:159], v[70:73], off offset:64
	v_pk_mul_f32 v[60:61], v[60:61], v[68:69]
	v_pk_mul_f32 v[58:59], v[58:59], v[66:67]
	global_store_dwordx4 v[158:159], v[58:61], off offset:512
	v_pk_mul_f32 v[56:57], v[56:57], v[64:65]
	v_pk_mul_f32 v[54:55], v[54:55], v[62:63]
	global_store_dwordx4 v[158:159], v[54:57], off offset:576
	v_add_u32_e32 v150, 0x24000, v174
	v_mov_b32_e32 v151, v3
	v_lshl_add_u64 v[158:159], v[150:151], 2, v[178:179]
	v_pk_mul_f32 v[52:53], v[52:53], v[84:85]
	v_pk_mul_f32 v[50:51], v[50:51], v[82:83]
	global_store_dwordx4 v[158:159], v[50:53], off
	v_pk_mul_f32 v[48:49], v[48:49], v[76:77]
	v_pk_mul_f32 v[46:47], v[46:47], v[74:75]
	global_store_dwordx4 v[158:159], v[46:49], off offset:64
	v_pk_mul_f32 v[44:45], v[44:45], v[68:69]
	v_pk_mul_f32 v[42:43], v[42:43], v[66:67]
	global_store_dwordx4 v[158:159], v[42:45], off offset:512
	v_pk_mul_f32 v[40:41], v[40:41], v[64:65]
	v_pk_mul_f32 v[38:39], v[38:39], v[62:63]
	global_store_dwordx4 v[158:159], v[38:41], off offset:576
	v_add_u32_e32 v150, 0x28000, v174
	v_mov_b32_e32 v151, v3
	v_lshl_add_u64 v[158:159], v[150:151], 2, v[178:179]
	v_pk_mul_f32 v[34:35], v[34:35], v[84:85]
	v_pk_mul_f32 v[32:33], v[32:33], v[82:83]
	global_store_dwordx4 v[158:159], v[32:35], off
	v_pk_mul_f32 v[30:31], v[30:31], v[76:77]
	v_pk_mul_f32 v[28:29], v[28:29], v[74:75]
	global_store_dwordx4 v[158:159], v[28:31], off offset:64
	v_pk_mul_f32 v[26:27], v[26:27], v[68:69]
	v_pk_mul_f32 v[24:25], v[24:25], v[66:67]
	global_store_dwordx4 v[158:159], v[24:27], off offset:512
	v_pk_mul_f32 v[22:23], v[22:23], v[64:65]
	v_pk_mul_f32 v[20:21], v[20:21], v[62:63]
	global_store_dwordx4 v[158:159], v[20:23], off offset:576
	v_add_u32_e32 v150, 0x2c000, v174
	v_mov_b32_e32 v151, v3
	v_lshl_add_u64 v[158:159], v[150:151], 2, v[178:179]
	v_pk_mul_f32 v[18:19], v[18:19], v[84:85]
	v_pk_mul_f32 v[16:17], v[16:17], v[82:83]
	global_store_dwordx4 v[158:159], v[16:19], off
	v_pk_mul_f32 v[14:15], v[14:15], v[76:77]
	v_pk_mul_f32 v[12:13], v[12:13], v[74:75]
	global_store_dwordx4 v[158:159], v[12:15], off offset:64
	v_pk_mul_f32 v[10:11], v[10:11], v[68:69]
	v_pk_mul_f32 v[8:9], v[8:9], v[66:67]
	global_store_dwordx4 v[158:159], v[8:11], off offset:512
	v_pk_mul_f32 v[6:7], v[6:7], v[64:65]
	v_pk_mul_f32 v[4:5], v[4:5], v[62:63]
	global_store_dwordx4 v[158:159], v[4:7], off offset:576
	s_branch .Lrk_tail

.LBB0_347:
	s_cmp_lt_i32 s18, 24
	s_cselect_b32 s7, s67, 0x3000
	s_cmp_gt_i32 s18, 15
	s_cselect_b32 s7, s7, 0
	v_lshl_or_b32 v134, s85, 8, v154
	s_lshl_b32 s7, s7, 2
	v_add_u32_e32 v2, v37, v134
	s_add_u32 s46, s79, s7
	s_addc_u32 s47, s80, 0
	v_ashrrev_i32_e32 v135, 31, v134
	v_lshl_add_u64 v[136:137], v[134:135], 2, s[46:47]
	global_load_dwordx4 v[146:149], v[136:137], off
	s_add_u32 s44, s0, s44
	s_addc_u32 s45, s1, s45
	global_load_dwordx4 v[142:145], v[136:137], off offset:64
	global_load_dwordx4 v[138:141], v[136:137], off offset:512
	s_nop 0
	global_load_dwordx4 v[134:137], v[136:137], off offset:576
	s_mov_b32 s85, s6
	s_mov_b64 s[46:47], s[16:17]
	s_mov_b32 s18, s12
	s_and_b64 vcc, exec, s[4:5]
	v_mov_b32_e32 v210, v2
	v_mov_b32_e32 v211, v3
	v_lshlrev_b64 v[210:211], 2, v[210:211]
	v_lshl_add_u64 v[212:213], s[38:39], 0, v[210:211]
	global_load_dwordx4 v[156:159], v[212:213], off
	global_load_dwordx4 v[166:169], v[212:213], off offset:64
	global_load_dwordx4 v[170:173], v[212:213], off offset:512
	global_load_dwordx4 v[174:177], v[212:213], off offset:576
	v_add_u32_e32 v210, 0x4000, v2
	v_mov_b32_e32 v211, v3
	v_lshlrev_b64 v[210:211], 2, v[210:211]
	v_lshl_add_u64 v[212:213], s[38:39], 0, v[210:211]
	global_load_dwordx4 v[178:181], v[212:213], off
	global_load_dwordx4 v[182:185], v[212:213], off offset:64
	global_load_dwordx4 v[186:189], v[212:213], off offset:512
	global_load_dwordx4 v[190:193], v[212:213], off offset:576
	v_add_u32_e32 v210, 0x8000, v2
	v_mov_b32_e32 v211, v3
	v_lshlrev_b64 v[210:211], 2, v[210:211]
	v_lshl_add_u64 v[212:213], s[38:39], 0, v[210:211]
	global_load_dwordx4 v[194:197], v[212:213], off
	global_load_dwordx4 v[198:201], v[212:213], off offset:64
	global_load_dwordx4 v[202:205], v[212:213], off offset:512
	global_load_dwordx4 v[206:209], v[212:213], off offset:576
	v_mov_b32_e32 v210, v2
	v_mov_b32_e32 v211, v3
	v_lshlrev_b64 v[210:211], 2, v[210:211]
	v_lshl_add_u64 v[214:215], s[44:45], 0, v[210:211]
	s_waitcnt vmcnt(11)
	v_pk_fma_f32 v[132:133], v[132:133], v[148:149], v[158:159]
	v_pk_fma_f32 v[130:131], v[130:131], v[146:147], v[156:157]
	global_store_dwordx4 v[214:215], v[130:133], off
	v_add_u32_e32 v210, 0xc000, v2
	v_mov_b32_e32 v211, v3
	v_lshlrev_b64 v[210:211], 2, v[210:211]
	v_lshl_add_u64 v[212:213], s[38:39], 0, v[210:211]
	global_load_dwordx4 v[156:159], v[212:213], off
	s_waitcnt vmcnt(12)
	v_pk_fma_f32 v[128:129], v[128:129], v[144:145], v[168:169]
	v_pk_fma_f32 v[126:127], v[126:127], v[142:143], v[166:167]
	global_store_dwordx4 v[214:215], v[126:129], off offset:64
	global_load_dwordx4 v[166:169], v[212:213], off offset:64
	s_waitcnt vmcnt(13)
	v_pk_fma_f32 v[124:125], v[124:125], v[140:141], v[172:173]
	v_pk_fma_f32 v[122:123], v[122:123], v[138:139], v[170:171]
	global_store_dwordx4 v[214:215], v[122:125], off offset:512
	global_load_dwordx4 v[170:173], v[212:213], off offset:512
	s_waitcnt vmcnt(14)
	v_pk_fma_f32 v[116:117], v[116:117], v[136:137], v[176:177]
	v_pk_fma_f32 v[114:115], v[114:115], v[134:135], v[174:175]
	global_store_dwordx4 v[214:215], v[114:117], off offset:576
	global_load_dwordx4 v[174:177], v[212:213], off offset:576
	v_add_u32_e32 v210, 0x4000, v2
	v_mov_b32_e32 v211, v3
	v_lshlrev_b64 v[210:211], 2, v[210:211]
	v_lshl_add_u64 v[214:215], s[44:45], 0, v[210:211]
	s_waitcnt vmcnt(15)
	v_pk_fma_f32 v[120:121], v[120:121], v[148:149], v[180:181]
	v_pk_fma_f32 v[118:119], v[118:119], v[146:147], v[178:179]
	global_store_dwordx4 v[214:215], v[118:121], off
	v_add_u32_e32 v210, 0x20000, v2
	v_mov_b32_e32 v211, v3
	v_lshlrev_b64 v[210:211], 2, v[210:211]
	v_lshl_add_u64 v[212:213], s[38:39], 0, v[210:211]
	global_load_dwordx4 v[178:181], v[212:213], off
	s_waitcnt vmcnt(16)
	v_pk_fma_f32 v[112:113], v[112:113], v[144:145], v[184:185]
	v_pk_fma_f32 v[110:111], v[110:111], v[142:143], v[182:183]
	global_store_dwordx4 v[214:215], v[110:113], off offset:64
	global_load_dwordx4 v[182:185], v[212:213], off offset:64
	s_waitcnt vmcnt(17)
	v_pk_fma_f32 v[108:109], v[108:109], v[140:141], v[188:189]
	v_pk_fma_f32 v[106:107], v[106:107], v[138:139], v[186:187]
	global_store_dwordx4 v[214:215], v[106:109], off offset:512
	global_load_dwordx4 v[186:189], v[212:213], off offset:512
	s_waitcnt vmcnt(18)
	v_pk_fma_f32 v[100:101], v[100:101], v[136:137], v[192:193]
	v_pk_fma_f32 v[98:99], v[98:99], v[134:135], v[190:191]
	global_store_dwordx4 v[214:215], v[98:101], off offset:576
	global_load_dwordx4 v[190:193], v[212:213], off offset:576
	v_add_u32_e32 v210, 0x8000, v2
	v_mov_b32_e32 v211, v3
	v_lshlrev_b64 v[210:211], 2, v[210:211]
	v_lshl_add_u64 v[214:215], s[44:45], 0, v[210:211]
	s_waitcnt vmcnt(19)
	v_pk_fma_f32 v[104:105], v[104:105], v[148:149], v[196:197]
	v_pk_fma_f32 v[102:103], v[102:103], v[146:147], v[194:195]
	global_store_dwordx4 v[214:215], v[102:105], off
	v_add_u32_e32 v210, 0x24000, v2
	v_mov_b32_e32 v211, v3
	v_lshlrev_b64 v[210:211], 2, v[210:211]
	v_lshl_add_u64 v[212:213], s[38:39], 0, v[210:211]
	global_load_dwordx4 v[194:197], v[212:213], off
	s_waitcnt vmcnt(20)
	v_pk_fma_f32 v[96:97], v[96:97], v[144:145], v[200:201]
	v_pk_fma_f32 v[94:95], v[94:95], v[142:143], v[198:199]
	global_store_dwordx4 v[214:215], v[94:97], off offset:64
	global_load_dwordx4 v[198:201], v[212:213], off offset:64
	s_waitcnt vmcnt(21)
	v_pk_fma_f32 v[92:93], v[92:93], v[140:141], v[204:205]
	v_pk_fma_f32 v[90:91], v[90:91], v[138:139], v[202:203]
	global_store_dwordx4 v[214:215], v[90:93], off offset:512
	global_load_dwordx4 v[202:205], v[212:213], off offset:512
	s_waitcnt vmcnt(22)
	v_pk_fma_f32 v[84:85], v[84:85], v[136:137], v[208:209]
	v_pk_fma_f32 v[82:83], v[82:83], v[134:135], v[206:207]
	global_store_dwordx4 v[214:215], v[82:85], off offset:576
	global_load_dwordx4 v[206:209], v[212:213], off offset:576
	v_add_u32_e32 v210, 0xc000, v2
	v_mov_b32_e32 v211, v3
	v_lshlrev_b64 v[210:211], 2, v[210:211]
	v_lshl_add_u64 v[214:215], s[44:45], 0, v[210:211]
	s_waitcnt vmcnt(22)
	v_pk_fma_f32 v[88:89], v[88:89], v[148:149], v[158:159]
	v_pk_fma_f32 v[86:87], v[86:87], v[146:147], v[156:157]
	global_store_dwordx4 v[214:215], v[86:89], off
	v_add_u32_e32 v210, 0x28000, v2
	v_mov_b32_e32 v211, v3
	v_lshlrev_b64 v[210:211], 2, v[210:211]
	v_lshl_add_u64 v[212:213], s[38:39], 0, v[210:211]
	global_load_dwordx4 v[156:159], v[212:213], off
	s_waitcnt vmcnt(22)
	v_pk_fma_f32 v[80:81], v[80:81], v[144:145], v[168:169]
	v_pk_fma_f32 v[78:79], v[78:79], v[142:143], v[166:167]
	global_store_dwordx4 v[214:215], v[78:81], off offset:64
	global_load_dwordx4 v[166:169], v[212:213], off offset:64
	s_waitcnt vmcnt(22)
	v_pk_fma_f32 v[76:77], v[76:77], v[140:141], v[172:173]
	v_pk_fma_f32 v[74:75], v[74:75], v[138:139], v[170:171]
	global_store_dwordx4 v[214:215], v[74:77], off offset:512
	global_load_dwordx4 v[170:173], v[212:213], off offset:512
	s_waitcnt vmcnt(22)
	v_pk_fma_f32 v[72:73], v[72:73], v[136:137], v[176:177]
	v_pk_fma_f32 v[70:71], v[70:71], v[134:135], v[174:175]
	global_store_dwordx4 v[214:215], v[70:73], off offset:576
	global_load_dwordx4 v[174:177], v[212:213], off offset:576
	v_add_u32_e32 v210, 0x20000, v2
	v_mov_b32_e32 v211, v3
	v_lshlrev_b64 v[210:211], 2, v[210:211]
	v_lshl_add_u64 v[214:215], s[44:45], 0, v[210:211]
	s_waitcnt vmcnt(22)
	v_pk_fma_f32 v[68:69], v[68:69], v[148:149], v[180:181]
	v_pk_fma_f32 v[66:67], v[66:67], v[146:147], v[178:179]
	global_store_dwordx4 v[214:215], v[66:69], off
	v_add_u32_e32 v210, 0x2c000, v2
	v_mov_b32_e32 v211, v3
	v_lshlrev_b64 v[210:211], 2, v[210:211]
	v_lshl_add_u64 v[212:213], s[38:39], 0, v[210:211]
	global_load_dwordx4 v[178:181], v[212:213], off
	s_waitcnt vmcnt(22)
	v_pk_fma_f32 v[64:65], v[64:65], v[144:145], v[184:185]
	v_pk_fma_f32 v[62:63], v[62:63], v[142:143], v[182:183]
	global_store_dwordx4 v[214:215], v[62:65], off offset:64
	global_load_dwordx4 v[182:185], v[212:213], off offset:64
	s_waitcnt vmcnt(22)
	v_pk_fma_f32 v[60:61], v[60:61], v[140:141], v[188:189]
	v_pk_fma_f32 v[58:59], v[58:59], v[138:139], v[186:187]
	global_store_dwordx4 v[214:215], v[58:61], off offset:512
	global_load_dwordx4 v[186:189], v[212:213], off offset:512
	s_waitcnt vmcnt(22)
	v_pk_fma_f32 v[52:53], v[52:53], v[136:137], v[192:193]
	v_pk_fma_f32 v[50:51], v[50:51], v[134:135], v[190:191]
	global_store_dwordx4 v[214:215], v[50:53], off offset:576
	global_load_dwordx4 v[190:193], v[212:213], off offset:576
	v_add_u32_e32 v210, 0x24000, v2
	v_mov_b32_e32 v211, v3
	v_lshlrev_b64 v[210:211], 2, v[210:211]
	v_lshl_add_u64 v[214:215], s[44:45], 0, v[210:211]
	s_waitcnt vmcnt(22)
	v_pk_fma_f32 v[56:57], v[56:57], v[148:149], v[196:197]
	v_pk_fma_f32 v[54:55], v[54:55], v[146:147], v[194:195]
	global_store_dwordx4 v[214:215], v[54:57], off
	s_waitcnt vmcnt(21)
	v_pk_fma_f32 v[48:49], v[48:49], v[144:145], v[200:201]
	v_pk_fma_f32 v[46:47], v[46:47], v[142:143], v[198:199]
	global_store_dwordx4 v[214:215], v[46:49], off offset:64
	s_waitcnt vmcnt(20)
	v_pk_fma_f32 v[44:45], v[44:45], v[140:141], v[204:205]
	v_pk_fma_f32 v[42:43], v[42:43], v[138:139], v[202:203]
	global_store_dwordx4 v[214:215], v[42:45], off offset:512
	s_waitcnt vmcnt(19)
	v_pk_fma_f32 v[34:35], v[34:35], v[136:137], v[208:209]
	v_pk_fma_f32 v[32:33], v[32:33], v[134:135], v[206:207]
	global_store_dwordx4 v[214:215], v[32:35], off offset:576
	v_add_u32_e32 v210, 0x28000, v2
	v_mov_b32_e32 v211, v3
	v_lshlrev_b64 v[210:211], 2, v[210:211]
	v_lshl_add_u64 v[214:215], s[44:45], 0, v[210:211]
	s_waitcnt vmcnt(18)
	v_pk_fma_f32 v[40:41], v[40:41], v[148:149], v[158:159]
	v_pk_fma_f32 v[38:39], v[38:39], v[146:147], v[156:157]
	global_store_dwordx4 v[214:215], v[38:41], off
	s_waitcnt vmcnt(17)
	v_pk_fma_f32 v[30:31], v[30:31], v[144:145], v[168:169]
	v_pk_fma_f32 v[28:29], v[28:29], v[142:143], v[166:167]
	global_store_dwordx4 v[214:215], v[28:31], off offset:64
	s_waitcnt vmcnt(16)
	v_pk_fma_f32 v[26:27], v[26:27], v[140:141], v[172:173]
	v_pk_fma_f32 v[24:25], v[24:25], v[138:139], v[170:171]
	global_store_dwordx4 v[214:215], v[24:27], off offset:512
	s_waitcnt vmcnt(15)
	v_pk_fma_f32 v[18:19], v[18:19], v[136:137], v[176:177]
	v_pk_fma_f32 v[16:17], v[16:17], v[134:135], v[174:175]
	global_store_dwordx4 v[214:215], v[16:19], off offset:576
	v_add_u32_e32 v210, 0x2c000, v2
	v_mov_b32_e32 v211, v3
	v_lshlrev_b64 v[210:211], 2, v[210:211]
	v_lshl_add_u64 v[214:215], s[44:45], 0, v[210:211]
	s_waitcnt vmcnt(14)
	v_pk_fma_f32 v[22:23], v[22:23], v[148:149], v[180:181]
	v_pk_fma_f32 v[20:21], v[20:21], v[146:147], v[178:179]
	global_store_dwordx4 v[214:215], v[20:23], off
	s_waitcnt vmcnt(13)
	v_pk_fma_f32 v[14:15], v[14:15], v[144:145], v[184:185]
	v_pk_fma_f32 v[12:13], v[12:13], v[142:143], v[182:183]
	global_store_dwordx4 v[214:215], v[12:15], off offset:64
	s_waitcnt vmcnt(12)
	v_pk_fma_f32 v[10:11], v[10:11], v[140:141], v[188:189]
	v_pk_fma_f32 v[8:9], v[8:9], v[138:139], v[186:187]
	global_store_dwordx4 v[214:215], v[8:11], off offset:512
	s_waitcnt vmcnt(11)
	v_pk_fma_f32 v[6:7], v[6:7], v[136:137], v[192:193]
	v_pk_fma_f32 v[4:5], v[4:5], v[134:135], v[190:191]
	global_store_dwordx4 v[214:215], v[4:7], off offset:576
	s_mov_b64 s[38:39], s[14:15]
	s_cbranch_vccnz .LBB0_363

.LBB0_398:
	s_or_b64 exec, exec, s[78:79]
	v_add_u32_e32 v7, 0xfffff120, v2
	s_movk_i32 s38, 0x580
	v_cmp_gt_u32_e32 vcc, s38, v7
	s_and_saveexec_b64 s[78:79], vcc
	v_mov_b64_e32 v[10:11], 0xf10000
	v_mov_b64_e32 v[12:13], 0x400
	v_mov_b32_e32 v11, 0x1600
	v_mov_b64_e32 v[4:5], s[86:87]
	v_mov_b32_e32 v6, v7
	s_or_b64 exec, exec, s[78:79]
	v_add_u32_e32 v7, 0xffffeba0, v2
	v_cmp_gt_u32_e32 vcc, s38, v7
	s_and_saveexec_b64 s[78:79], vcc
	v_mov_b64_e32 v[10:11], 0x1490000
	v_mov_b64_e32 v[12:13], 0x400
	v_mov_b32_e32 v11, 0x1600
	v_mov_b64_e32 v[4:5], s[88:89]
	v_mov_b32_e32 v6, v7
	s_or_b64 exec, exec, s[78:79]
	v_add_u32_e32 v7, 0xffffe620, v2
	v_cmp_gt_u32_e32 vcc, s38, v7
	s_and_saveexec_b64 s[78:79], vcc
	v_mov_b64_e32 v[10:11], 0x1a10000
	v_mov_b64_e32 v[12:13], 0x400
	v_mov_b32_e32 v11, 0x1600
	v_mov_b64_e32 v[4:5], s[90:91]
	v_mov_b32_e32 v6, v7
	s_or_b64 exec, exec, s[78:79]
	v_add_u32_e32 v7, 0xffffe0a0, v2
	v_cmp_gt_u32_e32 vcc, s38, v7
	s_and_saveexec_b64 s[78:79], vcc
	v_mov_b64_e32 v[10:11], 0x1f90000
	v_mov_b64_e32 v[12:13], 0x400
	v_mov_b32_e32 v11, 0x1600
	v_mov_b64_e32 v[4:5], s[92:93]
	v_mov_b32_e32 v6, v7
	s_or_b64 exec, exec, s[78:79]
	v_add_u32_e32 v7, 0xffffdb20, v2
	s_movk_i32 s38, 0x2c0
	v_cmp_gt_u32_e32 vcc, s38, v7
	s_and_saveexec_b64 s[78:79], vcc
	v_mov_b64_e32 v[10:11], 0x2510000
	v_mov_b64_e32 v[12:13], 0xb00
	v_mov_b32_e32 v11, 0x400
	v_mov_b64_e32 v[4:5], s[52:53]
	v_mov_b32_e32 v6, v7
	s_or_b64 exec, exec, s[78:79]
	v_add_u32_e32 v7, 0xffffd860, v2
	v_cmp_gt_u32_e32 vcc, s38, v7
	s_and_saveexec_b64 s[78:79], vcc
	v_mov_b64_e32 v[10:11], 0x27d0000
	v_mov_b64_e32 v[12:13], 0xb00
	v_mov_b32_e32 v11, 0x400
	v_mov_b64_e32 v[4:5], s[94:95]
	v_mov_b32_e32 v6, v7
	s_or_b64 exec, exec, s[78:79]
	v_add_u32_e32 v7, 0xffffd5a0, v2
	v_cmp_gt_u32_e32 vcc, s38, v7
	s_and_saveexec_b64 s[78:79], vcc
	v_mov_b64_e32 v[10:11], 0x2a90000
	v_mov_b64_e32 v[12:13], 0xb00
	v_mov_b32_e32 v11, 0x400
	v_mov_b64_e32 v[4:5], s[96:97]
	v_mov_b32_e32 v6, v7
	s_or_b64 exec, exec, s[78:79]
	s_movk_i32 s38, 0x2d1f
	v_cmp_lt_i32_e32 vcc, s38, v2
	s_and_saveexec_b64 s[78:79], vcc
	v_mov_b64_e32 v[10:11], 0x2d50000
	v_add_u32_e32 v6, 0xffffd2e0, v2
	v_mov_b64_e32 v[12:13], 0xb00
	v_mov_b32_e32 v11, 0x400
	v_mov_b64_e32 v[4:5], s[74:75]
	s_or_b64 exec, exec, s[78:79]
	v_cmp_lt_i32_e32 vcc, -1, v6
	s_mov_b64 s[82:83], 0
	s_and_saveexec_b64 s[78:79], vcc
	s_cbranch_execz .LBB0_426
	v_add_u32_e32 v2, 63, v11
	v_lshrrev_b32_e32 v2, 6, v2
	v_cvt_f32_u32_sdwa v7, v2 dst_sel:DWORD dst_unused:UNUSED_PAD src0_sel:WORD_0
	v_cvt_f32_u32_sdwa v8, v6 dst_sel:DWORD dst_unused:UNUSED_PAD src0_sel:WORD_0
	v_mov_b32_e32 v13, v0
	v_rcp_iflag_f32_e32 v9, v7
	v_lshlrev_b32_e32 v14, 2, v13
	v_and_b32_e32 v18, 60, v14
	v_mul_f32_e32 v9, v8, v9
	v_trunc_f32_e32 v9, v9
	v_cvt_u32_f32_e32 v14, v9
	v_fma_f32 v8, -v9, v7, v8
	v_cmp_ge_f32_e64 vcc, |v8|, v7
	v_mov_b32_e32 v8, 0
	v_mov_b32_e32 v9, 0
	v_addc_co_u32_e32 v7, vcc, 0, v14, vcc
	v_mul_lo_u16_e32 v2, v7, v2
	v_sub_u16_e32 v2, v6, v2
	v_lshlrev_b32_e32 v17, 6, v2
	v_or_b32_e32 v2, v17, v18
	v_cmp_lt_u32_e32 vcc, v2, v11
	v_lshlrev_b32_e32 v2, 2, v2
	v_lshlrev_b32_sdwa v16, v224, v7 dst_sel:DWORD dst_unused:UNUSED_PAD src0_sel:DWORD src1_sel:WORD_0
	v_lshl_add_u64 v[14:15], v[4:5], 0, v[2:3]
	v_bfe_u32 v2, v13, 4, 4
	v_mov_b32_e32 v4, 0
	v_mov_b32_e32 v6, 0
	v_mov_b32_e32 v7, 0
	v_mov_b32_e32 v80, 0
	v_mov_b32_e32 v81, 0
	v_mov_b32_e32 v82, 0
	v_mov_b32_e32 v83, 0
	v_mov_b32_e32 v84, 0
	v_mov_b32_e32 v85, 0
	v_mov_b32_e32 v86, 0
	v_mov_b32_e32 v87, 0
	v_mov_b32_e32 v88, 0
	v_mov_b32_e32 v89, 0
	v_mov_b32_e32 v90, 0
	v_mov_b32_e32 v91, 0
	v_mov_b32_e32 v92, 0
	v_mov_b32_e32 v93, 0
	v_mov_b32_e32 v94, 0
	v_mov_b32_e32 v95, 0
	s_and_saveexec_b64 s[82:83], vcc
	s_cbranch_execz .Lctca_skip
	v_or_b32_e32 v5, v16, v2
	v_mul_hi_u32_u24_e32 v7, v5, v11
	v_mul_u32_u24_e32 v6, v5, v11
	v_lshl_add_u64 v[6:7], v[6:7], 2, v[14:15]
	global_load_dwordx4 v[80:83], v[6:7], off nt
	v_or3_b32 v5, v2, v16, 16
	v_mul_hi_u32_u24_e32 v7, v5, v11
	v_mul_u32_u24_e32 v6, v5, v11
	v_lshl_add_u64 v[6:7], v[6:7], 2, v[14:15]
	global_load_dwordx4 v[84:87], v[6:7], off nt
	v_or3_b32 v5, v2, v16, 32
	v_mul_hi_u32_u24_e32 v7, v5, v11
	v_mul_u32_u24_e32 v6, v5, v11
	v_lshl_add_u64 v[6:7], v[6:7], 2, v[14:15]
	global_load_dwordx4 v[88:91], v[6:7], off nt
	v_or3_b32 v5, v2, v16, 48
	v_mul_hi_u32_u24_e32 v7, v5, v11
	v_mul_u32_u24_e32 v6, v5, v11
	v_lshl_add_u64 v[6:7], v[6:7], 2, v[14:15]
	global_load_dwordx4 v[92:95], v[6:7], off nt
.Lctca_skip:
	s_or_b64 exec, exec, s[82:83]
	v_mul_u32_u24_e32 v19, 0x104, v2
	v_lshlrev_b32_e32 v18, 2, v18
	v_add3_u32 v5, v28, v19, v18
	s_waitcnt vmcnt(3)
	ds_write2_b32 v5, v80, v81 offset1:1
	ds_write2_b32 v5, v82, v83 offset0:2 offset1:3
	v_add_u32_e32 v8, 0x1040, v5
	s_waitcnt vmcnt(2)
	ds_write2_b32 v8, v84, v85 offset1:1
	ds_write2_b32 v8, v86, v87 offset0:2 offset1:3
	v_add_u32_e32 v8, 0x2080, v5
	s_waitcnt vmcnt(1)
	ds_write2_b32 v8, v88, v89 offset1:1
	ds_write2_b32 v8, v90, v91 offset0:2 offset1:3
	v_add_u32_e32 v8, 0x30c0, v5
	s_waitcnt vmcnt(0)
	ds_write2_b32 v8, v92, v93 offset1:1
	ds_write2_b32 v8, v94, v95 offset0:2 offset1:3
	v_and_b32_e32 v4, 63, v13
	v_or_b32_e32 v5, v17, v4
	v_cmp_lt_u32_e32 vcc, v5, v11
	s_waitcnt lgkmcnt(0)
	s_barrier
	s_and_saveexec_b64 s[82:83], vcc
	s_cbranch_execz .LBB0_425
	v_lshlrev_b32_e32 v2, 1, v10
	v_lshl_add_u64 v[6:7], s[28:29], 0, v[2:3]
	v_lshrrev_b32_e32 v2, 3, v13
	v_mul_hi_u32_u24_e32 v9, v12, v5
	v_mul_u32_u24_e32 v8, v12, v5
	v_and_b32_e32 v13, 24, v2
	v_lshl_add_u64 v[6:7], v[8:9], 1, v[6:7]
	v_lshlrev_b32_e32 v2, 1, v16
	v_lshl_add_u64 v[8:9], v[6:7], 0, v[2:3]
	v_mul_u32_u24_e32 v2, 0x41, v13
	v_lshlrev_b32_e32 v2, 2, v2
	v_lshlrev_b32_e32 v4, 2, v4
	v_add3_u32 v12, v28, v2, v4
	v_add3_u32 v14, v28, v4, v2
	ds_read_b32 v6, v12
	ds_read2_b32 v[4:5], v14 offset0:65 offset1:130
	v_add_u32_e32 v2, 0x200, v14
	s_waitcnt lgkmcnt(0)
	v_cvt_pk_bf16_f32 v4, v6, v4
	ds_read2_b32 v[6:7], v2 offset0:67 offset1:132
	v_add_u32_e32 v2, 0x400, v14
	ds_read2_b32 v[10:11], v2 offset0:69 offset1:134
	ds_read_b32 v2, v14 offset:1820
	s_waitcnt lgkmcnt(2)
	v_cvt_pk_bf16_f32 v5, v5, v6
	s_waitcnt lgkmcnt(1)
	v_cvt_pk_bf16_f32 v6, v7, v10
	s_waitcnt lgkmcnt(0)
	v_cvt_pk_bf16_f32 v7, v11, v2
	v_lshlrev_b32_e32 v2, 1, v13
	v_lshl_add_u64 v[8:9], v[8:9], 0, v[2:3]
	global_store_dwordx4 v[8:9], v[4:7], off
	ds_read_b32 v2, v12 offset:8320
	s_nop 0
	v_add_u32_e32 v4, 0x2000, v14
	ds_read2_b32 v[4:5], v4 offset0:97 offset1:162
	s_waitcnt lgkmcnt(0)
	v_cvt_pk_bf16_f32 v4, v2, v4
	v_add_u32_e32 v2, 0x2200, v14
	ds_read2_b32 v[6:7], v2 offset0:99 offset1:164
	v_add_u32_e32 v2, 0x2400, v14
	ds_read2_b32 v[10:11], v2 offset0:101 offset1:166
	ds_read_b32 v2, v14 offset:10140
	s_waitcnt lgkmcnt(2)
	v_cvt_pk_bf16_f32 v5, v5, v6
	s_waitcnt lgkmcnt(1)
	v_cvt_pk_bf16_f32 v6, v7, v10
	s_waitcnt lgkmcnt(0)
	v_cvt_pk_bf16_f32 v7, v11, v2
	global_store_dwordx4 v[8:9], v[4:7], off offset:64
